# grid-barrier poll loops: s_sleep 1 -> s_sleep 0 (tighter polling)
# speedup vs baseline: 1.0018x; 1.0018x over previous
.LBB0_6:
	s_sleep 0
	global_load_dword v2, v1, s[6:7] sc1
	s_waitcnt vmcnt(0)
	v_cmp_gt_u32_e32 vcc, s33, v2
	s_cbranch_vccnz .LBB0_6

.LBB0_16:
	s_sleep 0
	global_load_dword v18, v0, s[2:3] offset:32 sc1
	s_waitcnt vmcnt(0)
	v_and_b32_e32 v18, 0xffff0000, v18
	v_cmp_ne_u32_e32 vcc, v18, v17
	s_or_b64 s[4:5], vcc, s[4:5]
	s_andn2_b64 exec, exec, s[4:5]
	s_cbranch_execnz .LBB0_16

.LBB0_61:
	s_sleep 0
	global_load_dword v1, v0, s[90:91] sc1
	s_waitcnt vmcnt(0)
	v_cmp_lt_u32_e32 vcc, v1, v185
	s_cbranch_vccnz .LBB0_61

.LBB0_171:
	s_sleep 0
	global_load_dword v2, v0, s[90:91] sc1
	s_waitcnt vmcnt(0)
	v_cmp_lt_u32_e32 vcc, v2, v1
	s_cbranch_vccnz .LBB0_171

.LBB0_244:
	s_sleep 0
	global_load_dword v1, v41, s[90:91] sc1
	s_waitcnt vmcnt(0)
	v_cmp_lt_u32_e32 vcc, v1, v0
	s_cbranch_vccnz .LBB0_244
	s_branch .LBB0_216

.LBB0_347:
	s_sleep 0
	global_load_dword v26, v1, s[90:91] sc1
	s_waitcnt vmcnt(0)
	v_cmp_lt_u32_e32 vcc, v26, v25
	s_cbranch_vccnz .LBB0_347

.LBB0_385:
	s_sleep 0
	global_load_dword v1, v73, s[90:91] sc1
	s_waitcnt vmcnt(0)
	v_cmp_lt_u32_e32 vcc, v1, v0
	s_cbranch_vccnz .LBB0_385
